# forgetting-attention interior loop: K / V / F tiles staged HBM->LDS with global_load_lds (LDS-DMA) instead of VGPR loads + ds_write
# speedup vs baseline: 1.0079x; 1.0017x over previous
.LBB0_265:
	v_pk_add_f32 v[50:51], v[50:51], v[144:145]
	v_pk_add_f32 v[52:53], v[52:53], v[36:37]
	v_pk_add_f32 v[54:55], v[54:55], v[38:39]
	v_pk_add_f32 v[56:57], v[56:57], v[40:41]
	v_pk_add_f32 v[58:59], v[58:59], v[42:43]
	v_pk_add_f32 v[60:61], v[60:61], v[44:45]
	v_pk_add_f32 v[62:63], v[62:63], v[46:47]
	v_add_f32_e32 v32, v48, v112
	v_add_f32_e32 v33, v49, v125
	v_pk_add_f32 v[50:51], v[50:51], v[52:53]
	v_pk_add_f32 v[54:55], v[54:55], v[56:57]
	v_pk_add_f32 v[58:59], v[58:59], v[60:61]
	v_add_f32_e32 v32, v32, v33
	v_pk_add_f32 v[50:51], v[50:51], v[54:55]
	v_pk_add_f32 v[58:59], v[58:59], v[62:63]
	v_pk_add_f32 v[50:51], v[50:51], v[58:59]
	v_add_f32_e32 v32, v32, v50
	v_add_f32_e32 v32, v32, v51
	s_add_i32 s18, s18, 1
	v_add_f32_e32 v136, v136, v32
	v_add_u32_e32 v143, 64, v143
	s_cmp_ge_i32 s18, s3
	v_add_u32_e32 v124, 64, v124
	s_waitcnt vmcnt(0)
	s_waitcnt lgkmcnt(0)
	s_barrier
	s_cbranch_scc1 .LBB0_274
.LBB0_266:
	v_mov_b64_e32 v[32:33], s[12:13]
	s_movk_i32 s4, 0x1200
	v_mad_i64_i32 v[32:33], s[0:1], v124, s4, v[32:33]
	v_mad_i64_i32 v[34:35], s[0:1], v143, s4, v[122:123]
	s_add_i32 s4, s2, s18
	s_and_b32 s4, s4, 1
	s_xor_b32 s4, s4, 1
	s_mulk_i32 s4, 0x5100
	s_add_i32 s4, s4, s36
	s_addk_i32 s4, 0x100
	s_mov_b64 s[100:101], 0x940
	v_lshl_add_u64 v[32:33], v[32:33], 0, s[100:101]
	s_mov_b32 m0, s4
	s_mov_b64 s[100:101], 0xd40
	global_load_lds_dwordx4 v[32:33], off
	v_lshl_add_u64 v[34:35], v[34:35], 0, s[100:101]
	s_add_i32 m0, s4, 0x3000
	s_and_b64 vcc, exec, s[38:39]
	global_load_lds_dwordx4 v[34:35], off
	v_ashrrev_i32_e32 v125, 31, v124
	s_cbranch_vccnz .LBB0_268
	v_lshl_add_u64 v[32:33], v[124:125], 2, s[70:71]
	s_add_i32 m0, s4, 0x5000
	s_sub_i32 m0, m0, s36
	s_nop 0
	global_load_lds_dword v[32:33], off

.LBB0_272:
	v_exp_f32_e32 v112, v32
	v_exp_f32_e32 v125, v33
	v_exp_f32_e32 v144, v34
	v_exp_f32_e32 v145, v35
	v_exp_f32_e32 v36, v36
	v_exp_f32_e32 v37, v37
	v_exp_f32_e32 v38, v38
	v_exp_f32_e32 v39, v39
	v_cvt_pk_bf16_f32 v146, v112, v125
	v_cvt_pk_bf16_f32 v147, v144, v145
	v_cvt_pk_bf16_f32 v148, v36, v37
	v_cvt_pk_bf16_f32 v149, v38, v39
	v_exp_f32_e32 v40, v40
	v_exp_f32_e32 v41, v41
	v_exp_f32_e32 v42, v42
	v_exp_f32_e32 v43, v43
	v_exp_f32_e32 v44, v44
	v_exp_f32_e32 v45, v45
	v_exp_f32_e32 v46, v46
	v_exp_f32_e32 v47, v47
	v_mfma_f32_32x32x16_bf16 v[0:15], v[146:149], v[118:121], v[0:15]
	v_cvt_pk_bf16_f32 v150, v40, v41
	v_cvt_pk_bf16_f32 v151, v42, v43
	v_cvt_pk_bf16_f32 v152, v44, v45
	v_cvt_pk_bf16_f32 v153, v46, v47
	v_exp_f32_e32 v48, v48
	v_exp_f32_e32 v49, v49
	v_exp_f32_e32 v50, v50
	s_waitcnt lgkmcnt(6)
	v_mfma_f32_32x32x16_bf16 v[16:31], v[146:149], v[114:117], v[16:31]
	v_exp_f32_e32 v51, v51
	v_exp_f32_e32 v52, v52
	v_exp_f32_e32 v53, v53
	v_exp_f32_e32 v54, v54
	v_exp_f32_e32 v55, v55
	v_cvt_pk_bf16_f32 v192, v48, v49
	v_cvt_pk_bf16_f32 v193, v50, v51
	v_mfma_f32_32x32x16_bf16 v[0:15], v[150:153], v[108:111], v[0:15]
	v_cvt_pk_bf16_f32 v194, v52, v53
	v_cvt_pk_bf16_f32 v195, v54, v55
	v_exp_f32_e32 v56, v56
	v_exp_f32_e32 v57, v57
	v_exp_f32_e32 v58, v58
	v_exp_f32_e32 v59, v59
	v_exp_f32_e32 v60, v60
	s_waitcnt lgkmcnt(4)
	v_mfma_f32_32x32x16_bf16 v[16:31], v[150:153], v[104:107], v[16:31]
	v_exp_f32_e32 v61, v61
	v_exp_f32_e32 v62, v62
	v_exp_f32_e32 v63, v63
	v_cvt_pk_bf16_f32 v32, v56, v57
	v_cvt_pk_bf16_f32 v33, v58, v59
	v_cvt_pk_bf16_f32 v34, v60, v61
	v_cvt_pk_bf16_f32 v35, v62, v63
	v_mfma_f32_32x32x16_bf16 v[0:15], v[192:195], v[100:103], v[0:15]
	s_xor_b32 s0, s4, 1
	s_mulk_i32 s0, 0x5100
	s_addk_i32 s0, 0x100
	s_add_i32 s1, s0, s36
	s_and_b64 vcc, exec, s[38:39]
	s_waitcnt lgkmcnt(2)
	v_mfma_f32_32x32x16_bf16 v[16:31], v[192:195], v[96:99], v[16:31]
	v_mfma_f32_32x32x16_bf16 v[0:15], v[32:35], v[88:91], v[0:15]
	s_waitcnt lgkmcnt(0)
	v_mfma_f32_32x32x16_bf16 v[16:31], v[32:35], v[92:95], v[16:31]
	s_branch .LBB0_265
